# QKV GEMM workgroup stagger removed (0 us per slot; both attention layers); otherwise v46
# speedup vs baseline: 1.0076x; 1.0019x over previous
; __device__ __forceinline__ void stagger_start(int slot, int us_per_slot) { const unsigned long long t0 = __builtin_amdgcn_s_memrealtime(), dt = (unsigned long long)(slot * us_per_slot) * 100ull;
;     while (__builtin_amdgcn_s_memrealtime() - t0 < dt) __builtin_amdgcn_s_sleep(32); }
; template <int L> __device__ __forceinline__ void layer_phases(Frame& F, const int lo, const int hi, const XcdBarrier& bar, const int bid) {
;     ...
;             stagger_start(bid & 3, STAG_US);
.LBB0_189:
	s_cmp_gt_i32 s56, 2
	s_cselect_b64 s[0:1], -1, 0
	s_cmp_lt_i32 s57, 3
	s_cselect_b64 s[4:5], -1, 0
	s_or_b64 s[0:1], s[0:1], s[4:5]
	s_and_b64 vcc, exec, s[0:1]
	s_cbranch_vccnz .LBB0_269
	s_add_i32 s0, 0, 0x20520
	v_mov_b32_e32 v0, s0
	ds_read_b64 v[0:1], v0
	s_memrealtime s[0:1]
	s_memrealtime s[6:7]
	s_and_b32 s3, s2, 3
	s_mov_b32 s5, 0
	s_mul_i32 s4, s3, 0x0
	s_waitcnt lgkmcnt(0)
	v_readfirstlane_b32 s16, v0
	s_sub_u32 s6, s6, s0
	v_readfirstlane_b32 s17, v1
	s_subb_u32 s7, s7, s1
	v_mov_b64_e32 v[0:1], s[4:5]
	v_cmp_ge_u64_e32 vcc, s[6:7], v[0:1]
	s_cbranch_vccnz .LBB0_193
	v_mov_b64_e32 v[0:1], s[4:5]

; __device__ __forceinline__ void stagger_start(int slot, int us_per_slot) { const unsigned long long t0 = __builtin_amdgcn_s_memrealtime(), dt = (unsigned long long)(slot * us_per_slot) * 100ull;
;     while (__builtin_amdgcn_s_memrealtime() - t0 < dt) __builtin_amdgcn_s_sleep(32); }
; template <int L> __device__ __forceinline__ void layer_phases(Frame& F, const int lo, const int hi, const XcdBarrier& bar, const int bid) {
;     ...
;             stagger_start(bid & 3, STAG_US);
.LBB0_3339:
	s_cmp_gt_i32 s56, 32
	s_cselect_b64 s[0:1], -1, 0
	s_cmp_lt_i32 s57, 33
	s_cselect_b64 s[4:5], -1, 0
	s_or_b64 s[0:1], s[0:1], s[4:5]
	s_and_b64 vcc, exec, s[0:1]
	s_cbranch_vccnz .LBB0_3419
	s_add_i32 s0, 0, 0x20520
	v_mov_b32_e32 v0, s0
	s_waitcnt lgkmcnt(0)
	ds_read_b64 v[0:1], v0
	s_memrealtime s[0:1]
	s_memrealtime s[6:7]
	s_and_b32 s3, s2, 3
	s_mov_b32 s5, 0
	s_mul_i32 s4, s3, 0x0
	s_waitcnt lgkmcnt(0)
	v_readfirstlane_b32 s16, v0
	s_sub_u32 s6, s6, s0
	v_readfirstlane_b32 s17, v1
	s_subb_u32 s7, s7, s1
	v_mov_b64_e32 v[0:1], s[4:5]
	v_cmp_ge_u64_e32 vcc, s[6:7], v[0:1]
	s_cbranch_vccnz .LBB0_3343
	v_mov_b64_e32 v[0:1], s[4:5]
